# recurrence waves at s_setprio 2 beside the 8-deep decode waves
# speedup vs baseline: 1.0475x; 1.0050x over previous
; __device__ __forceinline__ void scan_prompt_wave(const Params& P, unsigned char* lds, int b, int h, int quarter) {
;     ...
;     } else if (wave < 4) {
;         const int rl = quarter * 16 + wave * 4 + (lane >> 4), cl = lane & 15, c0 = cl * 4;
;         float* op = (float*)(P.ws + WS_ORAW) + (size_t)(b * SEQ) * RW + h * 64 + rl;
;         float4 S = make_float4(0.f, 0.f, 0.f, 0.f);
;         while (scw[0] < 1u) __builtin_amdgcn_s_sleep(1);
;         asm volatile("" ::: "memory");
;         StepIn r[4];
;         lds_load_step(r[0], (const float*)lds, c0, rl); lds_load_step(r[1], (const float*)lds + RSB_BLK, c0, rl); lds_load_step(r[2], (const float*)lds + 2 * RSB_BLK, c0, rl);
.LBB0_1226:
	s_setprio 2
	s_lshr_b32 s0, s56, 3
	s_and_b32 s0, s0, 3
	s_lshl_b32 s0, s0, 4
	s_lshl_b32 s3, s2, 2
	s_or_b32 s0, s3, s0
	v_lshrrev_b32_e32 v2, 4, v1
	v_or_b32_e32 v2, s0, v2
	v_lshlrev_b32_e32 v115, 2, v2
	v_and_b32_e32 v3, 15, v1
	v_lshlrev_b32_e32 v114, 4, v3
	v_and_b32_e32 v121, 3, v1
	v_bfe_u32 v124, v1, 2, 2
	v_lshl_add_u32 v124, v121, 2, v124
	v_mul_u32_u24_e32 v117, 0x610, v124
	v_add_u32_e32 v116, v117, v115
	v_cmp_eq_u32_e64 s[8:9], 1, v121
	v_cmp_eq_u32_e64 s[10:11], 2, v121
	v_cmp_eq_u32_e64 s[12:13], 3, v121
	s_mul_i32 s14, s33, 0x600000
	s_add_u32 s14, s78, s14
	s_addc_u32 s15, s79, 0
	s_lshl_b32 s16, s40, 8
	s_add_u32 s14, s14, s16
	s_addc_u32 s15, s15, 0
	s_add_u32 s14, s14, 0x1349cc00
	s_addc_u32 s15, s15, 0
	v_mul_u32_u24_e32 v124, 0x600, v124
	v_add_u32_e32 v124, v124, v115
	v_mov_b32_e32 v125, 0
	v_lshl_add_u64 v[122:123], s[14:15], 0, v[124:125]
	v_mov_b32_e32 v118, s41
	s_lshl_b32 s16, s2, 2
	s_add_i32 s16, s16, 0x23004
	v_mov_b32_e32 v119, s16
	s_mov_b32 s4, 0
	s_movk_i32 s5, 0x7000
	s_mov_b32 s42, 0
	s_mov_b32 s6, 2
	s_mov_b64 s[0:1], 0x6000
	v_mov_b32_e32 v4, 0
	v_mov_b32_e32 v5, 0
	v_mov_b32_e32 v6, 0
	v_mov_b32_e32 v7, 0
	v_mov_b32_e32 v110, v114
	v_mov_b32_e32 v111, v115
	v_add_u32_e32 v112, s5, v114
	v_add_u32_e32 v113, s5, v115
	ds_read_b128 v[8:11], v110
	ds_read_b128 v[24:27], v110 offset:1024
	ds_read_b128 v[12:15], v110 offset:256
	ds_read_b32 v28, v111 offset:1280
	ds_read_b128 v[20:23], v110 offset:768
	ds_read_b128 v[16:19], v110 offset:512
	ds_read_b128 v[30:33], v110 offset:1552
	ds_read_b128 v[46:49], v110 offset:2576
	ds_read_b128 v[34:37], v110 offset:1808
	ds_read_b32 v50, v111 offset:2832
	ds_read_b128 v[42:45], v110 offset:2320
	ds_read_b128 v[38:41], v110 offset:2064
	ds_read_b128 v[52:55], v110 offset:3104
	ds_read_b128 v[68:71], v110 offset:4128
	ds_read_b128 v[56:59], v110 offset:3360
	ds_read_b32 v72, v111 offset:4384
	ds_read_b128 v[64:67], v110 offset:3872
	ds_read_b128 v[60:63], v110 offset:3616

; __device__ __forceinline__ float scan_step_asm(float4& S, const StepIn& s) {
;     float o, d1, d2, t;
;     asm volatile(
;         "v_mul_f32 %5, %0, %8\n\t"  "v_mul_f32 %6, %0, %12\n\t"
;         "v_fmac_f32 %5, %1, %9\n\t" "v_fmac_f32 %6, %1, %13\n\t"
;         "v_fmac_f32 %5, %2, %10\n\t" "v_fmac_f32 %6, %2, %14\n\t"
;         "v_fmac_f32 %5, %3, %11\n\t" "v_fmac_f32 %6, %3, %15\n\t"
;         "v_mul_f32 %0, %0, %16\n\t" "v_mul_f32 %1, %1, %17\n\t"
;         "v_add_f32_dpp %5, %5, %5 quad_perm:[1,0,3,2] row_mask:0xf bank_mask:0xf\n\t"
;         "v_add_f32_dpp %6, %6, %6 quad_perm:[1,0,3,2] row_mask:0xf bank_mask:0xf\n\t"
;         "v_mul_f32 %2, %2, %18\n\t" "v_mul_f32 %3, %3, %19\n\t"
;         "v_add_f32_dpp %5, %5, %5 quad_perm:[2,3,0,1] row_mask:0xf bank_mask:0xf\n\t"
;         "v_add_f32_dpp %6, %6, %6 quad_perm:[2,3,0,1] row_mask:0xf bank_mask:0xf\n\t"
;         "v_fmac_f32 %0, %28, %20\n\t" "v_fmac_f32 %1, %28, %21\n\t"
;         "v_add_f32_dpp %5, %5, %5 row_ror:4 row_mask:0xf bank_mask:0xf\n\t"
;         "v_add_f32_dpp %6, %6, %6 row_ror:4 row_mask:0xf bank_mask:0xf\n\t"
;         "v_fmac_f32 %2, %28, %22\n\t" "v_fmac_f32 %3, %28, %23\n\t"
;         "v_add_f32_dpp %5, %5, %5 row_ror:8 row_mask:0xf bank_mask:0xf\n\t"
; __device__ __forceinline__ void scan_prompt_wave(const Params& P, unsigned char* lds, int b, int h, int quarter) {
;     ...
;         for (int c = 0; c < NCH; ++c) {
;             const float* bp = (const float*)(lds + (c % SC_NB) * SC_BUF); const float* bpn = (const float*)(lds + ((c + 1) % SC_NB) * SC_BUF);
;             float ov = 0.f;
; #pragma unroll
;             for (int s = 0; s < SCH; ++s) {
;                 if (s == SCH - 3 && c + 1 < NCH) { while (scw[0] < (unsigned)(c + 2)) __builtin_amdgcn_s_sleep(1); asm volatile("" ::: "memory"); }
;                 lds_load_step(r[(s + 3) & 3], (s + 3 < SCH) ? bp + (s + 3) * RSB_BLK : bpn + (s + 3 - SCH) * RSB_BLK, c0, rl); __builtin_amdgcn_sched_barrier(0);
;                 const float o = scan_step_asm(S, r[s & 3]); __builtin_amdgcn_sched_barrier(0);
;                 ov = (cl == s) ? o : ov;
;             }
;             op[(size_t)cl * RW] = ov;
;             op += (size_t)SCH * RW;
;             if (lane == 0) scw[1 + wave] = (unsigned)(c + 1);
;         }
;         *(float4*)(P.out + OUT_WKV_P + ((size_t)(b * RH + h) * HD + rl) * HD + c0) = S;
.Lscan_landed:
	ds_read_b128 v[8:11], v112
	ds_read_b128 v[24:27], v112 offset:1024
	ds_read_b128 v[12:15], v112 offset:256
	ds_read_b32 v28, v113 offset:1280
	ds_read_b128 v[20:23], v112 offset:768
	ds_read_b128 v[16:19], v112 offset:512
	v_mul_f32_e32 v108, v4, v30
	v_mul_f32_e32 v97, v4, v46
	v_fmac_f32_e32 v108, v5, v31
	v_fmac_f32_e32 v97, v5, v47
	v_fmac_f32_e32 v108, v6, v32
	v_fmac_f32_e32 v97, v6, v48
	v_fmac_f32_e32 v108, v7, v33
	v_fmac_f32_e32 v97, v7, v49
	v_mul_f32_e32 v4, v4, v34
	v_mul_f32_e32 v5, v5, v35
	v_add_f32_dpp v108, v108, v108 quad_perm:[1,0,3,2] row_mask:0xf bank_mask:0xf
	v_mul_f32_e32 v6, v6, v36
	v_mul_f32_e32 v7, v7, v37
	v_add_f32_dpp v108, v108, v108 quad_perm:[2,3,0,1] row_mask:0xf bank_mask:0xf
	v_fmac_f32_e32 v4, v50, v42
	v_fmac_f32_e32 v5, v50, v43
	v_add_f32_dpp v108, v108, v108 row_ror:4 row_mask:0xf bank_mask:0xf
	v_fmac_f32_e32 v6, v50, v44
	v_fmac_f32_e32 v7, v50, v45
	v_add_f32_dpp v108, v108, v108 row_ror:8 row_mask:0xf bank_mask:0xf
	v_fma_f32 v4, -v108, v38, v4
	v_fma_f32 v5, -v108, v39, v5
	v_fma_f32 v6, -v108, v40, v6
	v_fma_f32 v7, -v108, v41, v7
	s_waitcnt lgkmcnt(9)
	ds_read_b128 v[30:33], v112 offset:1552
	ds_read_b128 v[46:49], v112 offset:2576
	ds_read_b128 v[34:37], v112 offset:1808
	ds_read_b32 v50, v113 offset:2832
	ds_read_b128 v[42:45], v112 offset:2320
	ds_read_b128 v[38:41], v112 offset:2064
	v_mul_f32_e32 v108, v4, v52
	v_mul_f32_e32 v98, v4, v68
	v_fmac_f32_e32 v108, v5, v53
	v_fmac_f32_e32 v98, v5, v69
	v_fmac_f32_e32 v108, v6, v54
	v_fmac_f32_e32 v98, v6, v70
	v_fmac_f32_e32 v108, v7, v55
	v_fmac_f32_e32 v98, v7, v71
	v_mul_f32_e32 v4, v4, v56
	v_mul_f32_e32 v5, v5, v57
	v_add_f32_dpp v108, v108, v108 quad_perm:[1,0,3,2] row_mask:0xf bank_mask:0xf
	v_mul_f32_e32 v6, v6, v58
	v_mul_f32_e32 v7, v7, v59
	v_add_f32_dpp v108, v108, v108 quad_perm:[2,3,0,1] row_mask:0xf bank_mask:0xf
	v_fmac_f32_e32 v4, v72, v64
	v_fmac_f32_e32 v5, v72, v65
	v_add_f32_dpp v108, v108, v108 row_ror:4 row_mask:0xf bank_mask:0xf
	v_fmac_f32_e32 v6, v72, v66
	v_fmac_f32_e32 v7, v72, v67
	v_add_f32_dpp v108, v108, v108 row_ror:8 row_mask:0xf bank_mask:0xf
	v_fma_f32 v4, -v108, v60, v4
	v_fma_f32 v5, -v108, v61, v5
	v_fma_f32 v6, -v108, v62, v6
	v_fma_f32 v7, -v108, v63, v7
	ds_read_b128 v[52:55], v112 offset:3104
	ds_read_b128 v[68:71], v112 offset:4128
	ds_read_b128 v[56:59], v112 offset:3360
	ds_read_b32 v72, v113 offset:4384
	ds_read_b128 v[64:67], v112 offset:3872
	ds_read_b128 v[60:63], v112 offset:3616
	v_mul_f32_e32 v108, v4, v74
	v_mul_f32_e32 v99, v4, v90
	v_fmac_f32_e32 v108, v5, v75
	v_fmac_f32_e32 v99, v5, v91
	v_fmac_f32_e32 v108, v6, v76
	v_fmac_f32_e32 v99, v6, v92
	v_fmac_f32_e32 v108, v7, v77
	v_fmac_f32_e32 v99, v7, v93
	v_mul_f32_e32 v4, v4, v78
	v_mul_f32_e32 v5, v5, v79
	v_add_f32_dpp v108, v108, v108 quad_perm:[1,0,3,2] row_mask:0xf bank_mask:0xf
	v_mul_f32_e32 v6, v6, v80
	v_mul_f32_e32 v7, v7, v81
	v_add_f32_dpp v108, v108, v108 quad_perm:[2,3,0,1] row_mask:0xf bank_mask:0xf
	v_add_f32_dpp v100, v96, v96 row_ror:8 row_mask:0xf bank_mask:0x3
	v_add_f32_dpp v100, v98, v98 row_ror:8 row_mask:0xf bank_mask:0xc
	v_add_f32_dpp v108, v108, v108 row_ror:4 row_mask:0xf bank_mask:0xf
	v_add_f32_dpp v101, v97, v97 row_ror:8 row_mask:0xf bank_mask:0x3
	v_add_f32_dpp v101, v99, v99 row_ror:8 row_mask:0xf bank_mask:0xc
	v_add_f32_dpp v108, v108, v108 row_ror:8 row_mask:0xf bank_mask:0xf
	v_fmac_f32_e32 v4, v94, v86
	v_fmac_f32_e32 v5, v94, v87
	v_add_f32_dpp v105, v100, v100 row_half_mirror row_mask:0xf bank_mask:0x5
	v_add_f32_dpp v105, v101, v101 row_half_mirror row_mask:0xf bank_mask:0xa
	v_fmac_f32_e32 v6, v94, v88
	v_fmac_f32_e32 v7, v94, v89
	v_add_f32_dpp v105, v105, v105 quad_perm:[1,0,3,2] row_mask:0xf bank_mask:0xf
	v_fma_f32 v4, -v108, v82, v4
	v_fma_f32 v5, -v108, v83, v5
	v_fma_f32 v6, -v108, v84, v6
	v_fma_f32 v7, -v108, v85, v7
	v_add_f32_dpp v105, v105, v105 quad_perm:[2,3,0,1] row_mask:0xf bank_mask:0xf
	v_cndmask_b32_e64 v102, v102, v103, s[8:9]
	v_cndmask_b32_e64 v102, v102, v104, s[10:11]
	s_add_i32 s42, s42, 1
	s_mov_b32 s4, s5
	s_add_i32 s5, s5, 0x7000
	v_cndmask_b32_e64 v102, v102, v105, s[12:13]
	s_waitcnt lgkmcnt(15)
	s_cmp_eq_u32 s5, 0x23000
	s_cselect_b32 s5, 0, s5
	v_fmac_f32_e32 v102, v106, v107
	s_add_i32 s6, s42, 2
	s_min_u32 s6, s6, 0x100
	global_store_dword v[122:123], v102, off
	v_mov_b32_e32 v110, v112
	v_mov_b32_e32 v111, v113
	v_add_u32_e32 v112, s5, v114
	v_add_u32_e32 v113, s5, v115
	v_lshl_add_u64 v[122:123], v[122:123], 0, s[0:1]
	s_cmpk_lg_i32 s42, 0x100
	s_cbranch_scc1 .Lscan_chunk
	s_waitcnt lgkmcnt(0)
	v_mov_b32_e32 v2, v4
	v_mov_b32_e32 v98, v5
	v_mov_b32_e32 v99, v6
	v_mov_b32_e32 v100, v7
	v_lshrrev_b32_e32 v88, 2, v115
	v_mov_b32_e32 v89, 0
	v_lshrrev_b32_e32 v3, 2, v114
	s_setprio 0
	s_branch .LBB0_1249
